# last layer: skip in-projection ctx tiles whose PX columns nobody reads (ctx cols >= 1040)
# baseline (speedup 1.0000x reference)
.LBB0_224:
	s_andn2_b64 vcc, exec, s[0:1]
	s_cbranch_vccnz .LBB0_329
	v_readlane_b32 s0, v244, 12
	v_readlane_b32 s1, v244, 13
	s_mul_i32 s29, s96, 0x1400000
	s_mul_i32 s28, s96, 0x10400
	s_andn2_b64 vcc, exec, s[0:1]
	s_mul_i32 s92, s96, 0x2800
	s_cbranch_vccnz .LBB0_236
	v_readlane_b32 s0, v244, 14
	v_readlane_b32 s1, v244, 15
	v_mov_b32_e32 v49, v175
	s_mov_b64 s[42:43], s[68:69]
	s_andn2_b64 vcc, exec, s[0:1]
	v_readlane_b32 s98, v242, 47
	s_nop 3
	s_cmp_eq_u32 s98, 0
	s_cbranch_scc1 .Lcx_keep_a
	s_and_b32 s98, s2, 63
	s_cmp_gt_u32 s98, 12
	s_cbranch_scc1 .LBB0_235
.Lcx_keep_a:
	s_cbranch_vccnz .LBB0_235
	v_ashrrev_i32_e32 v5, 6, v49
	v_lshlrev_b32_e32 v0, 8, v5
	s_add_u32 s0, s42, s29
	v_ashrrev_i32_e32 v1, 31, v0
	s_addc_u32 s1, s43, 0
	v_lshlrev_b64 v[0:1], 1, v[0:1]
	v_lshl_add_u64 v[2:3], s[42:43], 0, v[0:1]
	v_lshl_add_u64 v[0:1], s[0:1], 0, v[0:1]
	s_movk_i32 s0, 0x140
	v_bfe_u32 v4, v49, 4, 2
	v_cmp_gt_i32_e64 s[40:41], s0, v49
	s_add_u32 s0, s42, s28
	v_lshlrev_b32_e32 v144, 4, v4
	s_addc_u32 s1, s43, 0
	v_lshl_add_u64 v[2:3], v[2:3], 0, v[144:145]
	s_mov_b64 s[4:5], 0x3800000
	s_add_u32 s0, s0, 0x15eb4000
	s_waitcnt vmcnt(0)
	v_lshl_add_u64 v[44:45], v[2:3], 0, s[4:5]
	s_addc_u32 s1, s1, 0
	s_lshl_b64 s[4:5], s[92:93], 2
	s_add_u32 s4, s42, s4
	v_lshl_add_u64 v[46:47], v[0:1], 0, v[144:145]
	v_lshlrev_b32_e32 v0, 5, v5
	s_addc_u32 s5, s43, s5
	v_and_b32_e32 v51, 15, v49
	v_lshl_or_b32 v0, v4, 2, v0
	s_add_u32 s44, s4, 0x15ea5000
	s_movk_i32 s4, 0x150
	v_lshlrev_b32_e32 v1, 2, v51
	s_addc_u32 s45, s5, 0
	v_mul_lo_u32 v0, v0, s4
	s_add_u32 s46, s42, 0x7900000
	v_add3_u32 v56, 0, v1, v0
	s_addc_u32 s47, s43, 0
	v_lshlrev_b32_e32 v57, 3, v49
	v_lshl_add_u32 v58, v49, 5, 0
	v_add_u32_e32 v59, 0x400, v56
	v_add_u32_e32 v60, 0x1400, v56
	v_add_u32_e32 v61, 0x1800, v56
	s_mov_b32 s4, s2
	s_mov_b32 s5, s2
	s_branch .LBB0_229

.LBB0_252:
	v_readlane_b32 s0, v244, 10
	v_readlane_b32 s1, v244, 11
	s_andn2_b64 vcc, exec, s[0:1]
	s_cbranch_vccnz .LBB0_263
	v_readlane_b32 s0, v244, 14
	v_readlane_b32 s1, v244, 15
	v_mov_b32_e32 v49, v175
	s_mov_b64 s[42:43], s[68:69]
	s_andn2_b64 vcc, exec, s[0:1]
	v_readlane_b32 s98, v242, 47
	s_nop 3
	s_cmp_eq_u32 s98, 0
	s_cbranch_scc1 .Lcx_keep_b
	s_and_b32 s98, s2, 63
	s_cmp_gt_u32 s98, 12
	s_cbranch_scc1 .LBB0_262
.Lcx_keep_b:
	s_cbranch_vccnz .LBB0_262
	v_ashrrev_i32_e32 v5, 6, v49
	v_lshlrev_b32_e32 v0, 8, v5
	s_add_u32 s0, s42, s29
	v_ashrrev_i32_e32 v1, 31, v0
	s_addc_u32 s1, s43, 0
	v_lshlrev_b64 v[0:1], 1, v[0:1]
	v_lshl_add_u64 v[2:3], s[42:43], 0, v[0:1]
	v_lshl_add_u64 v[0:1], s[0:1], 0, v[0:1]
	s_movk_i32 s0, 0x140
	v_bfe_u32 v4, v49, 4, 2
	v_cmp_gt_i32_e64 s[40:41], s0, v49
	s_add_u32 s0, s42, s28
	v_lshlrev_b32_e32 v144, 4, v4
	s_addc_u32 s1, s43, 0
	v_lshl_add_u64 v[2:3], v[2:3], 0, v[144:145]
	s_mov_b64 s[4:5], 0x3800000
	s_add_u32 s0, s0, 0x15eb4000
	s_waitcnt vmcnt(0)
	v_lshl_add_u64 v[44:45], v[2:3], 0, s[4:5]
	s_addc_u32 s1, s1, 0
	s_lshl_b64 s[4:5], s[92:93], 2
	s_add_u32 s4, s42, s4
	s_addc_u32 s5, s43, s5
	v_lshl_add_u64 v[46:47], v[0:1], 0, v[144:145]
	v_lshlrev_b32_e32 v0, 5, v5
	s_add_u32 s44, s4, 0x15ea5000
	v_and_b32_e32 v51, 15, v49
	v_lshl_or_b32 v0, v4, 2, v0
	s_addc_u32 s45, s5, 0
	s_movk_i32 s4, 0x150
	v_lshlrev_b32_e32 v1, 2, v51
	s_add_u32 s46, s42, 0x7900000
	v_mul_lo_u32 v0, v0, s4
	s_addc_u32 s47, s43, 0
	v_add3_u32 v56, 0, v1, v0
	v_lshlrev_b32_e32 v57, 3, v49
	v_lshl_add_u32 v58, v49, 5, 0
	s_mov_b32 s4, s2
	s_mov_b32 s5, s2
	s_branch .LBB0_256
